# P0 f32-to-bf16 conversion loops (x and mem): 8 / 4 loads in flight per thread with counted waits instead of load-wait-store per element group
# speedup vs baseline: 1.0079x; 1.0050x over previous
.LBB0_106:
	s_ashr_i32 s3, s2, 31
	s_lshl_b64 s[4:5], s[2:3], 8
	s_waitcnt vmcnt(0)
	v_ashrrev_i32_e32 v3, 31, v2
	v_lshl_add_u64 v[4:5], s[4:5], 0, v[2:3]
	s_mov_b64 s[4:5], 0x400000
	s_lshl_b64 s[10:11], s[26:27], 8
	v_cmp_gt_u64_e32 vcc, s[4:5], v[4:5]
	s_and_saveexec_b64 s[4:5], vcc
	s_cbranch_execz .LBB0_109
	s_lshl_b64 s[6:7], s[2:3], 12
	s_add_u32 s6, s12, s6
	s_addc_u32 s7, s13, s7
	v_lshl_add_u64 v[6:7], v[2:3], 4, s[6:7]
	s_lshl_b64 s[6:7], s[26:27], 12
	s_lshl_b64 s[8:9], s[2:3], 11
	s_add_u32 s8, s24, s8
	s_addc_u32 s9, s25, s9
	v_lshl_add_u64 v[8:9], v[2:3], 3, s[8:9]
	s_mov_b64 s[8:9], 0xd900000
	v_lshl_add_u64 v[6:7], v[6:7], 0, 8
	v_lshl_add_u64 v[8:9], v[8:9], 0, s[8:9]
	s_lshl_b64 s[8:9], s[26:27], 11
	s_mov_b64 s[18:19], 0
	s_mov_b64 s[20:21], 0x3fffff
	v_mov_b64_e32 v[10:11], v[4:5]
	s_mov_b64 s[28:29], exec
	s_lshl_b64 s[30:31], s[10:11], 3
	s_sub_u32 s22, s30, s10
	s_subb_u32 s23, s31, s11
.Lcvta_loop:
	v_lshl_add_u64 v[28:29], v[10:11], 0, s[22:23]
	v_cmp_ge_u64_e32 vcc, s[20:21], v[28:29]
	s_and_b64 exec, exec, vcc
	s_cbranch_execz .Lcvta_done
	global_load_dwordx4 v[32:35], v[6:7], off offset:-8
	v_lshl_add_u64 v[6:7], v[6:7], 0, s[6:7]
	global_load_dwordx4 v[36:39], v[6:7], off offset:-8
	v_lshl_add_u64 v[6:7], v[6:7], 0, s[6:7]
	global_load_dwordx4 v[40:43], v[6:7], off offset:-8
	v_lshl_add_u64 v[6:7], v[6:7], 0, s[6:7]
	global_load_dwordx4 v[44:47], v[6:7], off offset:-8
	v_lshl_add_u64 v[6:7], v[6:7], 0, s[6:7]
	global_load_dwordx4 v[48:51], v[6:7], off offset:-8
	v_lshl_add_u64 v[6:7], v[6:7], 0, s[6:7]
	global_load_dwordx4 v[52:55], v[6:7], off offset:-8
	v_lshl_add_u64 v[6:7], v[6:7], 0, s[6:7]
	global_load_dwordx4 v[56:59], v[6:7], off offset:-8
	v_lshl_add_u64 v[6:7], v[6:7], 0, s[6:7]
	global_load_dwordx4 v[60:63], v[6:7], off offset:-8
	v_lshl_add_u64 v[6:7], v[6:7], 0, s[6:7]
	v_lshl_add_u64 v[10:11], v[10:11], 0, s[30:31]
	s_waitcnt vmcnt(7)
	v_cvt_pk_bf16_f32 v32, v32, v33
	v_cvt_pk_bf16_f32 v33, v34, v35
	global_store_dwordx2 v[8:9], v[32:33], off
	v_lshl_add_u64 v[8:9], v[8:9], 0, s[8:9]
	s_waitcnt vmcnt(7)
	v_cvt_pk_bf16_f32 v36, v36, v37
	v_cvt_pk_bf16_f32 v37, v38, v39
	global_store_dwordx2 v[8:9], v[36:37], off
	v_lshl_add_u64 v[8:9], v[8:9], 0, s[8:9]
	s_waitcnt vmcnt(7)
	v_cvt_pk_bf16_f32 v40, v40, v41
	v_cvt_pk_bf16_f32 v41, v42, v43
	global_store_dwordx2 v[8:9], v[40:41], off
	v_lshl_add_u64 v[8:9], v[8:9], 0, s[8:9]
	s_waitcnt vmcnt(7)
	v_cvt_pk_bf16_f32 v44, v44, v45
	v_cvt_pk_bf16_f32 v45, v46, v47
	global_store_dwordx2 v[8:9], v[44:45], off
	v_lshl_add_u64 v[8:9], v[8:9], 0, s[8:9]
	s_waitcnt vmcnt(7)
	v_cvt_pk_bf16_f32 v48, v48, v49
	v_cvt_pk_bf16_f32 v49, v50, v51
	global_store_dwordx2 v[8:9], v[48:49], off
	v_lshl_add_u64 v[8:9], v[8:9], 0, s[8:9]
	s_waitcnt vmcnt(7)
	v_cvt_pk_bf16_f32 v52, v52, v53
	v_cvt_pk_bf16_f32 v53, v54, v55
	global_store_dwordx2 v[8:9], v[52:53], off
	v_lshl_add_u64 v[8:9], v[8:9], 0, s[8:9]
	s_waitcnt vmcnt(7)
	v_cvt_pk_bf16_f32 v56, v56, v57
	v_cvt_pk_bf16_f32 v57, v58, v59
	global_store_dwordx2 v[8:9], v[56:57], off
	v_lshl_add_u64 v[8:9], v[8:9], 0, s[8:9]
	s_waitcnt vmcnt(7)
	v_cvt_pk_bf16_f32 v60, v60, v61
	v_cvt_pk_bf16_f32 v61, v62, v63
	global_store_dwordx2 v[8:9], v[60:61], off
	v_lshl_add_u64 v[8:9], v[8:9], 0, s[8:9]
	s_branch .Lcvta_loop
.Lcvta_done:
	v_cmp_ge_u64_e32 vcc, s[20:21], v[10:11]
	s_and_b64 exec, s[28:29], vcc
	s_cbranch_execz .LBB0_109

.LBB0_109:
	s_or_b64 exec, exec, s[4:5]
	s_mov_b64 s[4:5], 0x80000
	v_cmp_gt_u64_e32 vcc, s[4:5], v[4:5]
	s_and_saveexec_b64 s[4:5], vcc
	s_cbranch_execz .LBB0_112
	s_lshl_b64 s[6:7], s[2:3], 12
	s_add_u32 s6, s14, s6
	s_addc_u32 s7, s15, s7
	v_lshl_add_u64 v[6:7], v[2:3], 4, s[6:7]
	s_lshl_b64 s[6:7], s[26:27], 12
	s_lshl_b64 s[8:9], s[2:3], 11
	s_add_u32 s8, s24, s8
	s_addc_u32 s9, s25, s9
	v_lshl_add_u64 v[8:9], v[2:3], 3, s[8:9]
	s_mov_b64 s[8:9], 0x17900000
	v_lshl_add_u64 v[6:7], v[6:7], 0, 8
	v_lshl_add_u64 v[8:9], v[8:9], 0, s[8:9]
	s_lshl_b64 s[8:9], s[26:27], 11
	s_mov_b64 s[14:15], 0
	s_mov_b64 s[18:19], 0x7ffff
	v_mov_b64_e32 v[10:11], v[4:5]
	s_mov_b64 s[28:29], exec
	s_lshl_b64 s[30:31], s[10:11], 2
	s_sub_u32 s22, s30, s10
	s_subb_u32 s23, s31, s11
.Lcvtb_loop:
	v_lshl_add_u64 v[28:29], v[10:11], 0, s[22:23]
	v_cmp_ge_u64_e32 vcc, s[18:19], v[28:29]
	s_and_b64 exec, exec, vcc
	s_cbranch_execz .Lcvtb_done
	global_load_dwordx4 v[32:35], v[6:7], off offset:-8
	v_lshl_add_u64 v[6:7], v[6:7], 0, s[6:7]
	global_load_dwordx4 v[36:39], v[6:7], off offset:-8
	v_lshl_add_u64 v[6:7], v[6:7], 0, s[6:7]
	global_load_dwordx4 v[40:43], v[6:7], off offset:-8
	v_lshl_add_u64 v[6:7], v[6:7], 0, s[6:7]
	global_load_dwordx4 v[44:47], v[6:7], off offset:-8
	v_lshl_add_u64 v[6:7], v[6:7], 0, s[6:7]
	v_lshl_add_u64 v[10:11], v[10:11], 0, s[30:31]
	s_waitcnt vmcnt(3)
	v_cvt_pk_bf16_f32 v32, v32, v33
	v_cvt_pk_bf16_f32 v33, v34, v35
	global_store_dwordx2 v[8:9], v[32:33], off
	v_lshl_add_u64 v[8:9], v[8:9], 0, s[8:9]
	s_waitcnt vmcnt(3)
	v_cvt_pk_bf16_f32 v36, v36, v37
	v_cvt_pk_bf16_f32 v37, v38, v39
	global_store_dwordx2 v[8:9], v[36:37], off
	v_lshl_add_u64 v[8:9], v[8:9], 0, s[8:9]
	s_waitcnt vmcnt(3)
	v_cvt_pk_bf16_f32 v40, v40, v41
	v_cvt_pk_bf16_f32 v41, v42, v43
	global_store_dwordx2 v[8:9], v[40:41], off
	v_lshl_add_u64 v[8:9], v[8:9], 0, s[8:9]
	s_waitcnt vmcnt(3)
	v_cvt_pk_bf16_f32 v44, v44, v45
	v_cvt_pk_bf16_f32 v45, v46, v47
	global_store_dwordx2 v[8:9], v[44:45], off
	v_lshl_add_u64 v[8:9], v[8:9], 0, s[8:9]
	s_branch .Lcvtb_loop
.Lcvtb_done:
	v_cmp_ge_u64_e32 vcc, s[18:19], v[10:11]
	s_and_b64 exec, s[28:29], vcc
	s_cbranch_execz .LBB0_112
